# lnmix: router-weight staging loop (8 serial load/wait/ds_write trips) replaced by 8 loads in flight + counted waits
# speedup vs baseline: 1.0146x; 1.0050x over previous
.LBB0_747:
	v_lshlrev_b32_e32 v38, 2, v0
	global_load_dwordx4 v[6:9], v38, s[76:77]
	v_add_u32_e32 v38, 0x2000, v38
	global_load_dwordx4 v[10:13], v38, s[76:77]
	v_add_u32_e32 v38, 0x2000, v38
	global_load_dwordx4 v[14:17], v38, s[76:77]
	v_add_u32_e32 v38, 0x2000, v38
	global_load_dwordx4 v[18:21], v38, s[76:77]
	v_add_u32_e32 v38, 0x2000, v38
	global_load_dwordx4 v[22:25], v38, s[76:77]
	v_add_u32_e32 v38, 0x2000, v38
	global_load_dwordx4 v[26:29], v38, s[76:77]
	v_add_u32_e32 v38, 0x2000, v38
	global_load_dwordx4 v[30:33], v38, s[76:77]
	v_add_u32_e32 v38, 0x2000, v38
	global_load_dwordx4 v[34:37], v38, s[76:77]
	s_waitcnt vmcnt(7)
	ds_write_b128 v4, v[6:9]
	s_waitcnt vmcnt(6)
	ds_write_b128 v4, v[10:13] offset:8192
	s_waitcnt vmcnt(5)
	ds_write_b128 v4, v[14:17] offset:16384
	s_waitcnt vmcnt(4)
	ds_write_b128 v4, v[18:21] offset:24576
	s_waitcnt vmcnt(3)
	ds_write_b128 v4, v[22:25] offset:32768
	s_waitcnt vmcnt(2)
	ds_write_b128 v4, v[26:29] offset:40960
	s_waitcnt vmcnt(1)
	ds_write_b128 v4, v[30:33] offset:49152
	s_waitcnt vmcnt(0)
	ds_write_b128 v4, v[34:37] offset:57344

.LBB0_1348:
	v_lshlrev_b32_e32 v38, 2, v0
	global_load_dwordx4 v[6:9], v38, s[4:5]
	v_add_u32_e32 v38, 0x2000, v38
	global_load_dwordx4 v[10:13], v38, s[4:5]
	v_add_u32_e32 v38, 0x2000, v38
	global_load_dwordx4 v[14:17], v38, s[4:5]
	v_add_u32_e32 v38, 0x2000, v38
	global_load_dwordx4 v[18:21], v38, s[4:5]
	v_add_u32_e32 v38, 0x2000, v38
	global_load_dwordx4 v[22:25], v38, s[4:5]
	v_add_u32_e32 v38, 0x2000, v38
	global_load_dwordx4 v[26:29], v38, s[4:5]
	v_add_u32_e32 v38, 0x2000, v38
	global_load_dwordx4 v[30:33], v38, s[4:5]
	v_add_u32_e32 v38, 0x2000, v38
	global_load_dwordx4 v[34:37], v38, s[4:5]
	s_waitcnt vmcnt(7)
	ds_write_b128 v4, v[6:9]
	s_waitcnt vmcnt(6)
	ds_write_b128 v4, v[10:13] offset:8192
	s_waitcnt vmcnt(5)
	ds_write_b128 v4, v[14:17] offset:16384
	s_waitcnt vmcnt(4)
	ds_write_b128 v4, v[18:21] offset:24576
	s_waitcnt vmcnt(3)
	ds_write_b128 v4, v[22:25] offset:32768
	s_waitcnt vmcnt(2)
	ds_write_b128 v4, v[26:29] offset:40960
	s_waitcnt vmcnt(1)
	ds_write_b128 v4, v[30:33] offset:49152
	s_waitcnt vmcnt(0)
	ds_write_b128 v4, v[34:37] offset:57344
